# wait-state hardening: MFMA result -> load-destination overlap padded to the compiler's 8 states (9 one/two-state nops); no functional change
# baseline (speedup 1.0000x reference)
; #define AH_LDK(c, bufi) do { kf[bufi][0] = *(const LAS bf16x8*)(lds + kaddr0 + (c) * kcs); kf[bufi][1] = *(const LAS bf16x8*)(lds + kaddr1 + (c) * kcs); \
;         kf[bufi][2] = *(const LAS bf16x8*)(lds + kaddr0 + (c) * kcs + 512); kf[bufi][3] = *(const LAS bf16x8*)(lds + kaddr1 + (c) * kcs + 512); } while (0)
; template <bool LOC> ...
;     ...
;     AH_LDK(0, 0);
; #pragma unroll
;     for (int c = 0; c < 8; ++c) {
;         if (c < 7) AH_LDK(c + 1, (c + 1) & 1);
;         __builtin_amdgcn_sched_barrier(0);
;         f32x4 t0 = (f32x4){0.f, 0.f, 0.f, 0.f}, t1 = (f32x4){0.f, 0.f, 0.f, 0.f};
;         t0 = __builtin_amdgcn_mfma_f32_16x16x32_bf16(kf[c & 1][0], q0, t0, 0, 0, 0); t1 = __builtin_amdgcn_mfma_f32_16x16x32_bf16(kf[c & 1][2], q0, t1, 0, 0, 0);
;         t0 = __builtin_amdgcn_mfma_f32_16x16x32_bf16(kf[c & 1][1], q1, t0, 0, 0, 0); t1 = __builtin_amdgcn_mfma_f32_16x16x32_bf16(kf[c & 1][3], q1, t1, 0, 0, 0);
; #pragma unroll
;         for (int e = 0; e < 8; ++e) { const float a = (e < 4) ? t0[e] : t1[e - 4];
;             if (LOC) { const float bv = bp[c * RPB_PITCH + e]; const bool ok = (e >= elo) && (e < elo + 16); s[c][e] = ok ? (a * SC + bv) : -INFINITY; }
;             else s[c][e] = a * SC; }
;         __builtin_amdgcn_sched_barrier(0);
;     }
.LBB0_296:
	s_or_b64 exec, exec, s[68:69]
	v_mov_b32_e32 v216, 0x3e38aa3b
	v_mov_b32_e32 v217, 0x3e38aa3b
	s_add_i32 s64, s64, -4
	s_min_u32 s64, s64, 56
	v_sub_u32_e32 v36, s64, v26
	v_lshl_add_u32 v24, v36, 13, v128
	v_add_u32_e32 v25, v24, v126
	s_waitcnt lgkmcnt(0)
	s_barrier
	v_add_u32_e32 v26, v24, v127
	ds_read_b128 v[30:33], v25
	ds_read_b128 v[38:41], v25 offset:512
	ds_read_b128 v[42:45], v26
	ds_read_b128 v[46:49], v26 offset:512
	ds_read_b128 v[50:53], v25 offset:8192
	ds_read_b128 v[54:57], v25 offset:8704
	ds_read_b128 v[58:61], v26 offset:8192
	ds_read_b128 v[62:65], v26 offset:8704
	s_sub_i32 s63, s64, s63
	v_lshl_add_u32 v24, s63, 8, v129
	v_add_u32_e32 v232, 0x77c, v24
	v_add_u32_e32 v233, 0xb7c, v24
	s_waitcnt lgkmcnt(7)
	v_mfma_f32_16x16x32_bf16 v[30:33], v[30:33], v[4:7], 0
	ds_read2_b32 v[34:35], v232 offset0:0 offset1:1
	s_waitcnt lgkmcnt(5)
	v_mfma_f32_16x16x32_bf16 v[30:33], v[42:45], v[0:3], v[30:33]
	v_mfma_f32_16x16x32_bf16 v[38:41], v[38:41], v[4:7], 0
	v_mfma_f32_16x16x32_bf16 v[38:41], v[46:49], v[0:3], v[38:41]
	ds_read2_b32 v[210:211], v232 offset0:2 offset1:3
	ds_read2_b32 v[212:213], v232 offset0:4 offset1:5
	ds_read2_b32 v[214:215], v232 offset0:6 offset1:7
	s_waitcnt lgkmcnt(0)
	s_nop 3
	v_pk_fma_f32 v[34:35], v[30:31], v[216:217], v[34:35]
	v_cndmask_b32_e64 v30, v222, v34, s[6:7]
	v_cndmask_b32_e64 v29, v222, v35, s[8:9]
	v_pk_fma_f32 v[210:211], v[32:33], v[216:217], v[210:211]
	v_cndmask_b32_e64 v32, v222, v210, s[10:11]
	v_cndmask_b32_e64 v31, v222, v211, s[12:13]
	v_pk_fma_f32 v[212:213], v[38:39], v[216:217], v[212:213]
	v_cndmask_b32_e64 v34, v222, v212, s[14:15]
	v_cndmask_b32_e64 v33, v222, v213, s[16:17]
	v_pk_fma_f32 v[214:215], v[40:41], v[216:217], v[214:215]
	v_cndmask_b32_e64 v43, v222, v214, s[18:19]
	v_cndmask_b32_e64 v41, v222, v215, s[20:21]
	ds_read_b128 v[44:47], v25 offset:16384
	ds_read_b128 v[66:69], v25 offset:16896
	ds_read_b128 v[100:103], v26 offset:16384
	ds_read_b128 v[152:155], v26 offset:16896
	v_mfma_f32_16x16x32_bf16 v[48:51], v[50:53], v[4:7], 0
	ds_read2_b32 v[38:39], v232 offset0:64 offset1:65
	v_mfma_f32_16x16x32_bf16 v[48:51], v[58:61], v[0:3], v[48:51]
	v_mfma_f32_16x16x32_bf16 v[52:55], v[54:57], v[4:7], 0
	v_mfma_f32_16x16x32_bf16 v[52:55], v[62:65], v[0:3], v[52:55]
	ds_read2_b32 v[210:211], v232 offset0:66 offset1:67
	ds_read2_b32 v[212:213], v232 offset0:68 offset1:69
	ds_read2_b32 v[214:215], v232 offset0:70 offset1:71
	s_waitcnt lgkmcnt(0)
	s_nop 4
	v_pk_fma_f32 v[38:39], v[48:49], v[216:217], v[38:39]
	v_cndmask_b32_e64 v37, v222, v38, s[6:7]
	v_cndmask_b32_e64 v35, v222, v39, s[8:9]
	v_pk_fma_f32 v[210:211], v[50:51], v[216:217], v[210:211]
	v_cndmask_b32_e64 v39, v222, v210, s[10:11]
	v_cndmask_b32_e64 v38, v222, v211, s[12:13]
	v_pk_fma_f32 v[212:213], v[52:53], v[216:217], v[212:213]
	v_cndmask_b32_e64 v42, v222, v212, s[14:15]
	v_cndmask_b32_e64 v40, v222, v213, s[16:17]
	v_pk_fma_f32 v[214:215], v[54:55], v[216:217], v[214:215]
	v_cndmask_b32_e64 v51, v222, v214, s[18:19]
	v_cndmask_b32_e64 v49, v222, v215, s[20:21]
	ds_read_b128 v[52:55], v25 offset:24576
	ds_read_b128 v[60:63], v25 offset:25088
	ds_read_b128 v[170:173], v26 offset:24576
	ds_read_b128 v[174:177], v26 offset:25088
	v_mfma_f32_16x16x32_bf16 v[44:47], v[44:47], v[4:7], 0
	v_mfma_f32_16x16x32_bf16 v[56:59], v[66:69], v[4:7], 0
	v_mfma_f32_16x16x32_bf16 v[64:67], v[100:103], v[0:3], v[44:47]
	s_nop 4
	s_nop 0
	ds_read2_b32 v[46:47], v232 offset0:128 offset1:129
	v_mfma_f32_16x16x32_bf16 v[68:71], v[152:155], v[0:3], v[56:59]
	ds_read2_b32 v[210:211], v232 offset0:130 offset1:131
	ds_read2_b32 v[212:213], v232 offset0:132 offset1:133
	ds_read2_b32 v[214:215], v232 offset0:134 offset1:135
	s_waitcnt lgkmcnt(0)
	v_pk_fma_f32 v[46:47], v[64:65], v[216:217], v[46:47]
	v_cndmask_b32_e64 v45, v222, v46, s[6:7]
	v_cndmask_b32_e64 v44, v222, v47, s[8:9]
	v_pk_fma_f32 v[210:211], v[66:67], v[216:217], v[210:211]
	v_cndmask_b32_e64 v47, v222, v210, s[10:11]
	v_cndmask_b32_e64 v46, v222, v211, s[12:13]
	v_pk_fma_f32 v[212:213], v[68:69], v[216:217], v[212:213]
	v_cndmask_b32_e64 v50, v222, v212, s[14:15]
	v_cndmask_b32_e64 v48, v222, v213, s[16:17]
	v_pk_fma_f32 v[214:215], v[70:71], v[216:217], v[214:215]
	v_cndmask_b32_e64 v59, v222, v214, s[18:19]
	v_cndmask_b32_e64 v57, v222, v215, s[20:21]
	ds_read_b128 v[68:71], v25 offset:32768
	ds_read_b128 v[100:103], v25 offset:33280
	ds_read_b128 v[152:155], v26 offset:32768
	ds_read_b128 v[178:181], v26 offset:33280
	v_mfma_f32_16x16x32_bf16 v[52:55], v[52:55], v[4:7], 0
	v_mfma_f32_16x16x32_bf16 v[64:67], v[170:173], v[0:3], v[52:55]
	v_mfma_f32_16x16x32_bf16 v[60:63], v[60:63], v[4:7], 0
	s_nop 4
	s_nop 0
	ds_read2_b32 v[54:55], v232 offset0:192 offset1:193
	ds_read2_b32 v[210:211], v232 offset0:194 offset1:195
	ds_read2_b32 v[212:213], v232 offset0:196 offset1:197
	ds_read2_b32 v[214:215], v232 offset0:198 offset1:199
	s_waitcnt lgkmcnt(0)
	v_pk_fma_f32 v[54:55], v[64:65], v[216:217], v[54:55]
	v_cndmask_b32_e64 v53, v222, v54, s[6:7]
	v_cndmask_b32_e64 v52, v222, v55, s[8:9]
	v_mfma_f32_16x16x32_bf16 v[60:63], v[174:177], v[0:3], v[60:63]
	v_pk_fma_f32 v[210:211], v[66:67], v[216:217], v[210:211]
	v_cndmask_b32_e64 v55, v222, v210, s[10:11]
	v_cndmask_b32_e64 v54, v222, v211, s[12:13]
	s_nop 3
	s_nop 0
	v_pk_fma_f32 v[212:213], v[60:61], v[216:217], v[212:213]
	v_cndmask_b32_e64 v58, v222, v212, s[14:15]
	v_cndmask_b32_e64 v56, v222, v213, s[16:17]
	v_pk_fma_f32 v[214:215], v[62:63], v[216:217], v[214:215]
	v_cndmask_b32_e64 v67, v222, v214, s[18:19]
	v_cndmask_b32_e64 v65, v222, v215, s[20:21]
	ds_read_b128 v[170:173], v25 offset:40960
	ds_read_b128 v[174:177], v25 offset:41472
	ds_read_b128 v[182:185], v26 offset:40960
	ds_read_b128 v[186:189], v26 offset:41472
	v_mfma_f32_16x16x32_bf16 v[60:63], v[68:71], v[4:7], 0
	v_mfma_f32_16x16x32_bf16 v[68:71], v[100:103], v[4:7], 0
	v_mfma_f32_16x16x32_bf16 v[100:103], v[152:155], v[0:3], v[60:63]
	s_nop 4
	s_nop 0
	ds_read2_b32 v[62:63], v233 offset0:0 offset1:1
	v_mfma_f32_16x16x32_bf16 v[68:71], v[178:181], v[0:3], v[68:71]
	ds_read2_b32 v[210:211], v233 offset0:2 offset1:3
	ds_read2_b32 v[212:213], v233 offset0:4 offset1:5
	ds_read2_b32 v[214:215], v233 offset0:6 offset1:7
	s_waitcnt lgkmcnt(0)
; #define LAS __attribute__((address_space(3)))
; __device__ __forceinline__ int kswz(int key) { return ((key >> 1) & 1) | (((key >> 3) & 3) << 1); }
; template <bool LOC> ...
;     ...
;     AH_LDK(0, 0);
; #pragma unroll
;     for (int c = 0; c < 8; ++c) {
;         if (c < 7) AH_LDK(c + 1, (c + 1) & 1);
;         __builtin_amdgcn_sched_barrier(0);
;         f32x4 t0 = (f32x4){0.f, 0.f, 0.f, 0.f}, t1 = (f32x4){0.f, 0.f, 0.f, 0.f};
;         t0 = __builtin_amdgcn_mfma_f32_16x16x32_bf16(kf[c & 1][0], q0, t0, 0, 0, 0); t1 = __builtin_amdgcn_mfma_f32_16x16x32_bf16(kf[c & 1][2], q0, t1, 0, 0, 0);
;         t0 = __builtin_amdgcn_mfma_f32_16x16x32_bf16(kf[c & 1][1], q1, t0, 0, 0, 0); t1 = __builtin_amdgcn_mfma_f32_16x16x32_bf16(kf[c & 1][3], q1, t1, 0, 0, 0);
; #pragma unroll
;         for (int e = 0; e < 8; ++e) { const float a = (e < 4) ? t0[e] : t1[e - 4];
;             if (LOC) { const float bv = bp[c * RPB_PITCH + e]; const bool ok = (e >= elo) && (e < elo + 16); s[c][e] = ok ? (a * SC + bv) : -INFINITY; }
;             else s[c][e] = a * SC; }
;         __builtin_amdgcn_sched_barrier(0);
;     }
; __device__ __forceinline__ void phase_mixer(const Params& p, LAS unsigned char* lds, int l, bool with_ctx, int G, int tid, int wave, int lane, int rep_attn, int rep_pool) {
;     ...
;             u32x4 kreg[4], vreg[4];
;             const bf16_t* ksrc = PB + (size_t)(ML + b * CT + (tid >> 3)) * PBW + 1024 + h * 64 + (tid & 7) * 8;
;             const bf16_t* vsrc = VT + (size_t)(h * 64 + (tid >> 5)) * VTP + ML + b * CT + (tid & 31) * 8;
; #pragma unroll
;             for (int ps = 0; ps < 4; ++ps) { kreg[ps] = *(const u32x4*)(ksrc + (size_t)(ps * 64) * PBW); vreg[ps] = *(const u32x4*)(vsrc + (size_t)(ps * 16) * VTP); }
;             __builtin_amdgcn_sched_barrier(0);
; #pragma unroll
;             for (int ps = 0; ps < 4; ++ps) { const int key = ps * 64 + (tid >> 3), d = ps * 16 + (tid >> 5);
;                 *(LAS u32x4*)(lds + AT_KC + key * 128 + ((((tid & 7) ^ kswz(key))) << 4)) = kreg[ps];
;                 *(LAS u32x4*)(lds + AT_VC + d * 512 + ((((tid & 31) ^ (d & 15))) << 4)) = vreg[ps]; }
	v_pk_fma_f32 v[62:63], v[100:101], v[216:217], v[62:63]
	v_cndmask_b32_e64 v61, v222, v62, s[6:7]
	v_cndmask_b32_e64 v60, v222, v63, s[8:9]
	v_pk_fma_f32 v[210:211], v[102:103], v[216:217], v[210:211]
	v_cndmask_b32_e64 v63, v222, v210, s[10:11]
	v_cndmask_b32_e64 v62, v222, v211, s[12:13]
	v_pk_fma_f32 v[212:213], v[68:69], v[216:217], v[212:213]
	v_cndmask_b32_e64 v66, v222, v212, s[14:15]
	v_cndmask_b32_e64 v64, v222, v213, s[16:17]
	v_pk_fma_f32 v[214:215], v[70:71], v[216:217], v[214:215]
	v_cndmask_b32_e64 v102, v222, v214, s[18:19]
	v_cndmask_b32_e64 v100, v222, v215, s[20:21]
	ds_read_b128 v[178:181], v25 offset:49152
	ds_read_b128 v[190:193], v25 offset:49664
	ds_read_b128 v[194:197], v26 offset:49152
	ds_read_b128 v[198:201], v26 offset:49664
	v_mfma_f32_16x16x32_bf16 v[68:71], v[170:173], v[4:7], 0
	v_mfma_f32_16x16x32_bf16 v[170:173], v[182:185], v[0:3], v[68:71]
	v_mfma_f32_16x16x32_bf16 v[152:155], v[174:177], v[4:7], 0
	s_nop 4
	s_nop 0
	ds_read2_b32 v[70:71], v233 offset0:64 offset1:65
	ds_read2_b32 v[210:211], v233 offset0:66 offset1:67
	ds_read2_b32 v[212:213], v233 offset0:68 offset1:69
	ds_read2_b32 v[214:215], v233 offset0:70 offset1:71
	s_waitcnt lgkmcnt(0)
	v_pk_fma_f32 v[70:71], v[170:171], v[216:217], v[70:71]
	v_cndmask_b32_e64 v69, v222, v70, s[6:7]
	v_cndmask_b32_e64 v68, v222, v71, s[8:9]
	v_mfma_f32_16x16x32_bf16 v[174:177], v[186:189], v[0:3], v[152:155]
	v_pk_fma_f32 v[210:211], v[172:173], v[216:217], v[210:211]
	v_cndmask_b32_e64 v71, v222, v210, s[10:11]
	v_cndmask_b32_e64 v70, v222, v211, s[12:13]
	s_nop 3
	s_nop 0
	v_pk_fma_f32 v[212:213], v[174:175], v[216:217], v[212:213]
	v_cndmask_b32_e64 v101, v222, v212, s[14:15]
	v_cndmask_b32_e64 v99, v222, v213, s[16:17]
	v_pk_fma_f32 v[214:215], v[176:177], v[216:217], v[214:215]
	v_cndmask_b32_e64 v155, v222, v214, s[18:19]
	v_cndmask_b32_e64 v153, v222, v215, s[20:21]
	ds_read_b128 v[182:185], v25 offset:57344
	ds_read_b128 v[186:189], v25 offset:57856
	ds_read_b128 v[202:205], v26 offset:57344
	ds_read_b128 v[206:209], v26 offset:57856
	v_mfma_f32_16x16x32_bf16 v[170:173], v[178:181], v[4:7], 0
	ds_read2_b32 v[26:27], v233 offset0:128 offset1:129
	v_mfma_f32_16x16x32_bf16 v[170:173], v[194:197], v[0:3], v[170:173]
	v_mfma_f32_16x16x32_bf16 v[174:177], v[190:193], v[4:7], 0
	v_mfma_f32_16x16x32_bf16 v[174:177], v[198:201], v[0:3], v[174:177]
	ds_read2_b32 v[210:211], v233 offset0:130 offset1:131
	ds_read2_b32 v[212:213], v233 offset0:132 offset1:133
	ds_read2_b32 v[214:215], v233 offset0:134 offset1:135
	s_waitcnt lgkmcnt(0)
	s_nop 4
	v_pk_fma_f32 v[26:27], v[170:171], v[216:217], v[26:27]
	v_cndmask_b32_e64 v104, v222, v26, s[6:7]
	v_cndmask_b32_e64 v103, v222, v27, s[8:9]
	v_pk_fma_f32 v[210:211], v[172:173], v[216:217], v[210:211]
	v_cndmask_b32_e64 v151, v222, v210, s[10:11]
	v_cndmask_b32_e64 v105, v222, v211, s[12:13]
	v_pk_fma_f32 v[212:213], v[174:175], v[216:217], v[212:213]
	v_cndmask_b32_e64 v154, v222, v212, s[14:15]
	v_cndmask_b32_e64 v152, v222, v213, s[16:17]
	v_pk_fma_f32 v[214:215], v[176:177], v[216:217], v[214:215]
	v_cndmask_b32_e64 v175, v222, v214, s[18:19]
	v_cndmask_b32_e64 v173, v222, v215, s[20:21]
	v_mfma_f32_16x16x32_bf16 v[176:179], v[182:185], v[4:7], 0
	v_mfma_f32_16x16x32_bf16 v[4:7], v[186:189], v[4:7], 0
	v_mfma_f32_16x16x32_bf16 v[176:179], v[202:205], v[0:3], v[176:179]
	v_mfma_f32_16x16x32_bf16 v[0:3], v[206:209], v[0:3], v[4:7]
	s_nop 5
	ds_read2_b32 v[4:5], v233 offset0:192 offset1:193
	ds_read2_b32 v[210:211], v233 offset0:194 offset1:195
	ds_read2_b32 v[212:213], v233 offset0:196 offset1:197
	ds_read2_b32 v[214:215], v233 offset0:198 offset1:199
	s_waitcnt lgkmcnt(0)
	v_pk_fma_f32 v[4:5], v[176:177], v[216:217], v[4:5]
	v_cndmask_b32_e64 v170, v222, v4, s[6:7]
	v_cndmask_b32_e64 v167, v222, v5, s[8:9]
	v_pk_fma_f32 v[210:211], v[178:179], v[216:217], v[210:211]
	v_cndmask_b32_e64 v172, v222, v210, s[10:11]
	v_cndmask_b32_e64 v171, v222, v211, s[12:13]
	v_pk_fma_f32 v[212:213], v[0:1], v[216:217], v[212:213]
	v_cndmask_b32_e64 v176, v222, v212, s[14:15]
	v_cndmask_b32_e64 v174, v222, v213, s[16:17]
	v_pk_fma_f32 v[214:215], v[2:3], v[216:217], v[214:215]
	v_cndmask_b32_e64 v178, v222, v214, s[18:19]
	v_cndmask_b32_e64 v177, v222, v215, s[20:21]
	s_barrier
	s_add_i32 s94, s61, s3
	s_cmpk_gt_i32 s94, 0x7ff
	s_cbranch_scc1 .Lm_noctx
	s_lshr_b32 s95, s94, 8
	s_lshl_b32 s95, s95, 8
	s_add_i32 s95, s95, 0x8000
	s_mul_i32 s97, s95, 0xc00
	s_and_b32 s98, s94, 7
	s_lshl_b32 s99, s98, 7
	s_add_i32 s97, s97, s99
	s_add_i32 s97, s97, 0x800
	s_add_u32 s34, s0, s97
	s_addc_u32 s35, s1, 0
	s_lshl_b32 s99, s87, 10
	s_add_i32 m0, s99, 0x0
	s_nop 0
	global_load_lds_dwordx4 v235, s[34:35]
	s_add_u32 s34, s34, 0x30000
	s_addc_u32 s35, s35, 0
	s_add_i32 m0, s99, 0x2000
	s_nop 0
	global_load_lds_dwordx4 v235, s[34:35]
	s_add_u32 s34, s34, 0x30000
	s_addc_u32 s35, s35, 0
	s_add_i32 m0, s99, 0x4000
	s_nop 0
	global_load_lds_dwordx4 v235, s[34:35]
	s_add_u32 s34, s34, 0x30000
	s_addc_u32 s35, s35, 0
	s_add_i32 m0, s99, 0x6000
	s_nop 0
	global_load_lds_dwordx4 v235, s[34:35]
	s_mul_i32 s97, s98, 0x444000
	s_lshl_b32 s95, s95, 1
	s_add_i32 s97, s97, s95
	s_add_u32 s34, s28, s97
	s_addc_u32 s35, s29, 0
	s_add_i32 m0, s99, 0x8000
	s_nop 0
	global_load_lds_dwordx4 v236, s[34:35]
	s_add_u32 s34, s34, 0x111000
	s_addc_u32 s35, s35, 0
	s_add_i32 m0, s99, 0xa000
	s_nop 0
	global_load_lds_dwordx4 v236, s[34:35]
	s_add_u32 s34, s34, 0x111000
	s_addc_u32 s35, s35, 0
	s_add_i32 m0, s99, 0xc000
	s_nop 0
	global_load_lds_dwordx4 v236, s[34:35]
	s_add_u32 s34, s34, 0x111000
	s_addc_u32 s35, s35, 0
	s_add_i32 m0, s99, 0xe000
	s_nop 0
	global_load_lds_dwordx4 v236, s[34:35]

; #define AH_LDK(c, bufi) do { kf[bufi][0] = *(const LAS bf16x8*)(lds + kaddr0 + (c) * kcs); kf[bufi][1] = *(const LAS bf16x8*)(lds + kaddr1 + (c) * kcs); \
;         kf[bufi][2] = *(const LAS bf16x8*)(lds + kaddr0 + (c) * kcs + 512); kf[bufi][3] = *(const LAS bf16x8*)(lds + kaddr1 + (c) * kcs + 512); } while (0)
; template <bool LOC> ...
;     ...
;     AH_LDK(0, 0);
; #pragma unroll
;     for (int c = 0; c < 8; ++c) {
;         if (c < 7) AH_LDK(c + 1, (c + 1) & 1);
;         __builtin_amdgcn_sched_barrier(0);
;         f32x4 t0 = (f32x4){0.f, 0.f, 0.f, 0.f}, t1 = (f32x4){0.f, 0.f, 0.f, 0.f};
;         t0 = __builtin_amdgcn_mfma_f32_16x16x32_bf16(kf[c & 1][0], q0, t0, 0, 0, 0); t1 = __builtin_amdgcn_mfma_f32_16x16x32_bf16(kf[c & 1][2], q0, t1, 0, 0, 0);
;         t0 = __builtin_amdgcn_mfma_f32_16x16x32_bf16(kf[c & 1][1], q1, t0, 0, 0, 0); t1 = __builtin_amdgcn_mfma_f32_16x16x32_bf16(kf[c & 1][3], q1, t1, 0, 0, 0);
; #pragma unroll
;         for (int e = 0; e < 8; ++e) { const float a = (e < 4) ? t0[e] : t1[e - 4];
;             if (LOC) { const float bv = bp[c * RPB_PITCH + e]; const bool ok = (e >= elo) && (e < elo + 16); s[c][e] = ok ? (a * SC + bv) : -INFINITY; }
;             else s[c][e] = a * SC; }
;         __builtin_amdgcn_sched_barrier(0);
;     }
;     ...
;     float m2 = mx;
; #pragma unroll
;     for (int c = 0; c < 8; ++c)
; #pragma unroll
;         for (int e = 0; e < 8; ++e) m2 = fmaxf(m2, s[c][e]);
;     m2 = fmaxf(m2, __shfl_xor(m2, 16)); m2 = fmaxf(m2, __shfl_xor(m2, 32));
.Lqjoin_299:
	ds_read_b128 v[8:11], v132
	ds_read_b128 v[12:15], v132 offset:512
	ds_read_b128 v[16:19], v133
	ds_read_b128 v[20:23], v133 offset:512
	ds_read_b128 v[24:27], v132 offset:4096
	ds_read_b128 v[28:31], v132 offset:4608
	ds_read_b128 v[32:35], v133 offset:4096
	ds_read_b128 v[36:39], v133 offset:4608
	s_waitcnt lgkmcnt(7)
	v_mfma_f32_16x16x32_bf16 v[8:11], v[8:11], v[4:7], 0
	s_waitcnt lgkmcnt(5)
	v_mfma_f32_16x16x32_bf16 v[68:71], v[16:19], v[0:3], v[8:11]
	v_mfma_f32_16x16x32_bf16 v[8:11], v[12:15], v[4:7], 0
	s_waitcnt lgkmcnt(4)
	v_mfma_f32_16x16x32_bf16 v[64:67], v[20:23], v[0:3], v[8:11]
	s_nop 4
	s_nop 0
	ds_read_b128 v[8:11], v132 offset:8192
	ds_read_b128 v[12:15], v132 offset:8704
	ds_read_b128 v[16:19], v133 offset:8192
	ds_read_b128 v[20:23], v133 offset:8704
	s_waitcnt lgkmcnt(4)
	v_mfma_f32_16x16x32_bf16 v[24:27], v[24:27], v[4:7], 0
	v_mfma_f32_16x16x32_bf16 v[60:63], v[32:35], v[0:3], v[24:27]
	v_mfma_f32_16x16x32_bf16 v[24:27], v[28:31], v[4:7], 0
	v_mfma_f32_16x16x32_bf16 v[56:59], v[36:39], v[0:3], v[24:27]
	s_nop 4
	s_nop 1
	ds_read_b128 v[24:27], v132 offset:12288
	ds_read_b128 v[28:31], v132 offset:12800
	ds_read_b128 v[32:35], v133 offset:12288
	ds_read_b128 v[36:39], v133 offset:12800
	s_waitcnt lgkmcnt(4)
	v_mfma_f32_16x16x32_bf16 v[8:11], v[8:11], v[4:7], 0
	v_mfma_f32_16x16x32_bf16 v[52:55], v[16:19], v[0:3], v[8:11]
	v_mfma_f32_16x16x32_bf16 v[8:11], v[12:15], v[4:7], 0
	v_mfma_f32_16x16x32_bf16 v[48:51], v[20:23], v[0:3], v[8:11]
	s_nop 4
	s_nop 1
	ds_read_b128 v[8:11], v132 offset:16384
	ds_read_b128 v[12:15], v132 offset:16896
	ds_read_b128 v[16:19], v133 offset:16384
	ds_read_b128 v[20:23], v133 offset:16896
	s_waitcnt lgkmcnt(4)
	v_mfma_f32_16x16x32_bf16 v[24:27], v[24:27], v[4:7], 0
	v_mfma_f32_16x16x32_bf16 v[44:47], v[32:35], v[0:3], v[24:27]
	v_mfma_f32_16x16x32_bf16 v[24:27], v[28:31], v[4:7], 0
	v_mfma_f32_16x16x32_bf16 v[40:43], v[36:39], v[0:3], v[24:27]
	s_nop 4
	s_nop 1
	ds_read_b128 v[24:27], v132 offset:20480
	ds_read_b128 v[152:155], v132 offset:20992
	ds_read_b128 v[28:31], v133 offset:20480
	ds_read_b128 v[170:173], v133 offset:20992
	s_waitcnt lgkmcnt(4)
	v_mfma_f32_16x16x32_bf16 v[8:11], v[8:11], v[4:7], 0
	v_mfma_f32_16x16x32_bf16 v[36:39], v[16:19], v[0:3], v[8:11]
	v_mfma_f32_16x16x32_bf16 v[8:11], v[12:15], v[4:7], 0
	v_mfma_f32_16x16x32_bf16 v[32:35], v[20:23], v[0:3], v[8:11]
	s_nop 4
	s_nop 1
	ds_read_b128 v[8:11], v132 offset:24576
	ds_read_b128 v[12:15], v132 offset:25088
	ds_read_b128 v[16:19], v133 offset:24576
	ds_read_b128 v[174:177], v133 offset:25088
	s_waitcnt lgkmcnt(4)
	v_mfma_f32_16x16x32_bf16 v[20:23], v[24:27], v[4:7], 0
	v_mfma_f32_16x16x32_bf16 v[28:31], v[28:31], v[0:3], v[20:23]
	v_mfma_f32_16x16x32_bf16 v[20:23], v[152:155], v[4:7], 0
	v_mfma_f32_16x16x32_bf16 v[24:27], v[170:173], v[0:3], v[20:23]
	s_nop 4
	ds_read_b128 v[152:155], v132 offset:28672
	ds_read_b128 v[170:173], v132 offset:29184
	ds_read_b128 v[178:181], v133 offset:28672
	ds_read_b128 v[182:185], v133 offset:29184
	s_waitcnt lgkmcnt(0)
	v_mfma_f32_16x16x32_bf16 v[8:11], v[8:11], v[4:7], 0
	v_mfma_f32_16x16x32_bf16 v[20:23], v[16:19], v[0:3], v[8:11]
	v_mfma_f32_16x16x32_bf16 v[8:11], v[12:15], v[4:7], 0
	v_mfma_f32_16x16x32_bf16 v[16:19], v[174:177], v[0:3], v[8:11]
	s_nop 4
	v_mfma_f32_16x16x32_bf16 v[8:11], v[152:155], v[4:7], 0
	v_mfma_f32_16x16x32_bf16 v[12:15], v[178:181], v[0:3], v[8:11]
	v_mfma_f32_16x16x32_bf16 v[8:11], v[170:173], v[4:7], 0
	v_mfma_f32_16x16x32_bf16 v[8:11], v[182:185], v[0:3], v[8:11]
	s_nop 4
	s_mov_b32 s30, 0xff800000
	v_max3_f32 v97, v68, s30, v69
	v_max3_f32 v97, v97, v70, v71
	v_max3_f32 v97, v97, v64, v65
	v_max3_f32 v97, v97, v66, v67
	v_max3_f32 v97, v97, v60, v61
	v_max3_f32 v97, v97, v62, v63
	v_max3_f32 v97, v97, v56, v57
	v_max3_f32 v97, v97, v58, v59
	v_max3_f32 v97, v97, v52, v53
	v_max3_f32 v97, v97, v54, v55
	v_max3_f32 v97, v97, v48, v49
	v_max3_f32 v97, v97, v50, v51
	v_max3_f32 v97, v97, v44, v45
	v_max3_f32 v97, v97, v46, v47
	v_max3_f32 v97, v97, v40, v41
	v_max3_f32 v97, v97, v42, v43
	v_max3_f32 v97, v97, v36, v37
	v_max3_f32 v97, v97, v38, v39
	v_max3_f32 v97, v97, v32, v33
	v_max3_f32 v97, v97, v34, v35
	v_max3_f32 v97, v97, v28, v29
	v_max3_f32 v97, v97, v30, v31
	v_max3_f32 v97, v97, v24, v25
	v_max3_f32 v97, v97, v26, v27
	v_max3_f32 v97, v97, v20, v21
	v_max3_f32 v97, v97, v22, v23
	v_max3_f32 v97, v97, v16, v17
	v_max3_f32 v97, v97, v18, v19
	v_max3_f32 v97, v97, v12, v13
	v_max3_f32 v97, v97, v14, v15
	v_max3_f32 v97, v97, v8, v9
	v_max3_f32 v97, v97, v10, v11
	v_mul_f32_e32 v97, 0x3e38aa3b, v97
	ds_bpermute_b32 v99, v114, v97
	ds_read_b128 v[152:155], v134 offset:32768
	ds_read_b128 v[170:173], v134 offset:40960
	ds_read_b128 v[174:177], v134 offset:49152
	ds_read_b128 v[178:181], v134 offset:57344
	ds_read_b128 v[182:185], v135 offset:32768
	ds_read_b128 v[186:189], v135 offset:40960
	ds_read_b128 v[190:193], v135 offset:49152
	ds_read_b128 v[194:197], v135 offset:57344
	s_waitcnt lgkmcnt(8)
	v_max_f32_e32 v99, v99, v99
	v_max_f32_e32 v97, v97, v99
	ds_bpermute_b32 v99, v115, v97
	s_waitcnt lgkmcnt(0)
; __device__ __forceinline__ unsigned cvt_pk_bf16(float lo, float hi) { const f32x2 v = (f32x2){lo, hi}; return __builtin_bit_cast(unsigned, __builtin_convertvector(v, bf16v2)); }
; #define AH_LDV(c, bufi) do { const int vaddr = vrow + (((vchunk0 + (c) * vcs + g) ^ qi) << 4); _Pragma("unroll") for (int dt = 0; dt < 4; ++dt) vf[bufi][dt] = *(const LAS bf16x8*)(lds + vaddr + dt * vpitch_dt); } while (0)
; template <bool LOC> ...
;     ...
;     const float alpha = __builtin_amdgcn_exp2f(mx - m2);
;     mx = m2; lsum *= alpha;
; #pragma unroll
;     for (int dt = 0; dt < 4; ++dt) o[dt] = o[dt] * alpha;
;     bf16x8 vf[2][4];
;     ...
;     AH_LDV(0, 0);
; #pragma unroll
;     for (int c = 0; c < 8; ++c) {
;         if (c < 7) AH_LDV(c + 1, (c + 1) & 1);
;         __builtin_amdgcn_sched_barrier(0);
;         float pe[8];
; #pragma unroll
;         for (int e = 0; e < 8; ++e) { pe[e] = __builtin_amdgcn_exp2f(s[c][e] - mx); lsum += pe[e]; }
;         u32x4 pw; pw.x = cvt_pk_bf16(pe[0], pe[1]); pw.y = cvt_pk_bf16(pe[2], pe[3]); pw.z = cvt_pk_bf16(pe[4], pe[5]); pw.w = cvt_pk_bf16(pe[6], pe[7]);
;         const bf16x8 pb = __builtin_bit_cast(bf16x8, pw);
; #pragma unroll
;         for (int dt = 0; dt < 4; ++dt) o[dt] = __builtin_amdgcn_mfma_f32_16x16x32_bf16(vf[c & 1][dt], pb, o[dt], 0, 0, 0);
;         __builtin_amdgcn_sched_barrier(0);
;     }
	v_max_f32_e32 v99, v99, v99
	v_max_f32_e32 v97, v97, v99
	v_sub_f32_e32 v99, 0xff800000, v97
	v_exp_f32_e32 v99, v99
	s_nop 0
	v_mul_f32_e32 v198, 0, v99
	v_mov_b32_e32 v199, v198
	v_mov_b32_e32 v200, v198
	v_mov_b32_e32 v201, v198
	v_mov_b32_e32 v206, v97
	v_mov_b32_e32 v207, v97
	v_mov_b32_e32 v208, s67
	v_mov_b32_e32 v209, s67
	v_mov_b32_e32 v210, 0
	v_mov_b32_e32 v211, 0
	v_pk_fma_f32 v[68:69], v[68:69], v[208:209], v[206:207] neg_lo:[0,0,1] neg_hi:[0,0,1]
	v_pk_fma_f32 v[70:71], v[70:71], v[208:209], v[206:207] neg_lo:[0,0,1] neg_hi:[0,0,1]
	v_exp_f32_e32 v68, v68
	v_pk_fma_f32 v[64:65], v[64:65], v[208:209], v[206:207] neg_lo:[0,0,1] neg_hi:[0,0,1]
	v_exp_f32_e32 v69, v69
	v_pk_fma_f32 v[66:67], v[66:67], v[208:209], v[206:207] neg_lo:[0,0,1] neg_hi:[0,0,1]
	v_exp_f32_e32 v70, v70
	v_exp_f32_e32 v71, v71
	v_exp_f32_e32 v212, v64
	v_pk_add_f32 v[210:211], v[210:211], v[68:69]
	v_exp_f32_e32 v213, v65
	v_pk_add_f32 v[210:211], v[210:211], v[70:71]
	v_exp_f32_e32 v214, v66
	v_exp_f32_e32 v215, v67
	v_pk_add_f32 v[210:211], v[210:211], v[212:213]
	v_cvt_pk_bf16_f32 v64, v68, v69
	v_pk_add_f32 v[210:211], v[210:211], v[214:215]
	v_cvt_pk_bf16_f32 v65, v70, v71
	v_cvt_pk_bf16_f32 v66, v212, v213
	v_cvt_pk_bf16_f32 v67, v214, v215
	s_nop 1
	v_mfma_f32_16x16x32_bf16 v[68:71], v[152:155], v[64:67], v[198:201]
	v_mfma_f32_16x16x32_bf16 v[152:155], v[170:173], v[64:67], v[198:201]
	v_mfma_f32_16x16x32_bf16 v[170:173], v[174:177], v[64:67], v[198:201]
	v_mfma_f32_16x16x32_bf16 v[64:67], v[178:181], v[64:67], v[198:201]
	ds_read_b128 v[174:177], v136 offset:32768
	ds_read_b128 v[178:181], v136 offset:40960
	s_nop 0
	ds_read_b128 v[198:201], v136 offset:49152
	ds_read_b128 v[202:205], v136 offset:57344
	v_pk_fma_f32 v[60:61], v[60:61], v[208:209], v[206:207] neg_lo:[0,0,1] neg_hi:[0,0,1]
	v_pk_fma_f32 v[62:63], v[62:63], v[208:209], v[206:207] neg_lo:[0,0,1] neg_hi:[0,0,1]
	v_exp_f32_e32 v60, v60
	v_pk_fma_f32 v[56:57], v[56:57], v[208:209], v[206:207] neg_lo:[0,0,1] neg_hi:[0,0,1]
	v_exp_f32_e32 v61, v61
	v_pk_fma_f32 v[58:59], v[58:59], v[208:209], v[206:207] neg_lo:[0,0,1] neg_hi:[0,0,1]
	v_exp_f32_e32 v62, v62
	v_exp_f32_e32 v63, v63
	v_exp_f32_e32 v212, v56
	v_pk_add_f32 v[210:211], v[210:211], v[60:61]
	v_exp_f32_e32 v213, v57
	v_pk_add_f32 v[210:211], v[210:211], v[62:63]
	v_exp_f32_e32 v214, v58
	v_exp_f32_e32 v215, v59
	v_pk_add_f32 v[210:211], v[210:211], v[212:213]
	v_cvt_pk_bf16_f32 v56, v60, v61
	v_pk_add_f32 v[210:211], v[210:211], v[214:215]
	v_cvt_pk_bf16_f32 v57, v62, v63
	v_cvt_pk_bf16_f32 v58, v212, v213
	v_cvt_pk_bf16_f32 v59, v214, v215
	s_nop 1
	v_mfma_f32_16x16x32_bf16 v[60:63], v[182:185], v[56:59], v[68:71]
	v_mfma_f32_16x16x32_bf16 v[68:71], v[186:189], v[56:59], v[152:155]
	v_mfma_f32_16x16x32_bf16 v[152:155], v[190:193], v[56:59], v[170:173]
	v_mfma_f32_16x16x32_bf16 v[56:59], v[194:197], v[56:59], v[64:67]
	s_nop 2
	ds_read_b128 v[64:67], v137 offset:32768
	ds_read_b128 v[170:173], v137 offset:40960
	ds_read_b128 v[182:185], v137 offset:49152
	ds_read_b128 v[186:189], v137 offset:57344
	v_pk_fma_f32 v[52:53], v[52:53], v[208:209], v[206:207] neg_lo:[0,0,1] neg_hi:[0,0,1]
	v_pk_fma_f32 v[54:55], v[54:55], v[208:209], v[206:207] neg_lo:[0,0,1] neg_hi:[0,0,1]
	v_exp_f32_e32 v52, v52
	v_pk_fma_f32 v[48:49], v[48:49], v[208:209], v[206:207] neg_lo:[0,0,1] neg_hi:[0,0,1]
	v_exp_f32_e32 v53, v53
	v_pk_fma_f32 v[50:51], v[50:51], v[208:209], v[206:207] neg_lo:[0,0,1] neg_hi:[0,0,1]
	v_exp_f32_e32 v54, v54
	v_exp_f32_e32 v55, v55
	v_exp_f32_e32 v212, v48
	v_pk_add_f32 v[210:211], v[210:211], v[52:53]
	v_exp_f32_e32 v213, v49
	v_pk_add_f32 v[210:211], v[210:211], v[54:55]
	v_exp_f32_e32 v214, v50
	v_exp_f32_e32 v215, v51
	v_pk_add_f32 v[210:211], v[210:211], v[212:213]
	v_cvt_pk_bf16_f32 v48, v52, v53
	v_pk_add_f32 v[210:211], v[210:211], v[214:215]
	v_cvt_pk_bf16_f32 v49, v54, v55
	v_cvt_pk_bf16_f32 v50, v212, v213
	v_cvt_pk_bf16_f32 v51, v214, v215
	s_waitcnt lgkmcnt(4)
	s_nop 0
	v_mfma_f32_16x16x32_bf16 v[52:55], v[174:177], v[48:51], v[60:63]
	v_mfma_f32_16x16x32_bf16 v[60:63], v[178:181], v[48:51], v[68:71]
	v_mfma_f32_16x16x32_bf16 v[68:71], v[198:201], v[48:51], v[152:155]
	v_mfma_f32_16x16x32_bf16 v[48:51], v[202:205], v[48:51], v[56:59]
	s_nop 2
	ds_read_b128 v[56:59], v138 offset:32768
	ds_read_b128 v[152:155], v138 offset:40960
	ds_read_b128 v[174:177], v138 offset:49152
	ds_read_b128 v[178:181], v138 offset:57344
	v_pk_fma_f32 v[44:45], v[44:45], v[208:209], v[206:207] neg_lo:[0,0,1] neg_hi:[0,0,1]
	v_pk_fma_f32 v[46:47], v[46:47], v[208:209], v[206:207] neg_lo:[0,0,1] neg_hi:[0,0,1]
	v_exp_f32_e32 v44, v44
	v_pk_fma_f32 v[40:41], v[40:41], v[208:209], v[206:207] neg_lo:[0,0,1] neg_hi:[0,0,1]
	v_exp_f32_e32 v45, v45
	v_pk_fma_f32 v[42:43], v[42:43], v[208:209], v[206:207] neg_lo:[0,0,1] neg_hi:[0,0,1]
	v_exp_f32_e32 v46, v46
	v_exp_f32_e32 v47, v47
	v_exp_f32_e32 v212, v40
	v_pk_add_f32 v[210:211], v[210:211], v[44:45]
	v_exp_f32_e32 v213, v41
	v_pk_add_f32 v[210:211], v[210:211], v[46:47]
	v_exp_f32_e32 v214, v42
	v_exp_f32_e32 v215, v43
	v_pk_add_f32 v[210:211], v[210:211], v[212:213]
	v_cvt_pk_bf16_f32 v40, v44, v45
	v_pk_add_f32 v[210:211], v[210:211], v[214:215]
	v_cvt_pk_bf16_f32 v41, v46, v47
	v_cvt_pk_bf16_f32 v42, v212, v213
	v_cvt_pk_bf16_f32 v43, v214, v215
	s_waitcnt lgkmcnt(4)
	s_nop 0
	v_mfma_f32_16x16x32_bf16 v[44:47], v[64:67], v[40:43], v[52:55]
	v_mfma_f32_16x16x32_bf16 v[52:55], v[170:173], v[40:43], v[60:63]
	v_mfma_f32_16x16x32_bf16 v[60:63], v[182:185], v[40:43], v[68:71]
	v_mfma_f32_16x16x32_bf16 v[40:43], v[186:189], v[40:43], v[48:51]
	s_nop 2
	ds_read_b128 v[48:51], v139 offset:32768
	ds_read_b128 v[64:67], v139 offset:40960
	ds_read_b128 v[68:71], v139 offset:49152
	ds_read_b128 v[170:173], v139 offset:57344
	s_and_b64 vcc, exec, s[74:75]
	s_cbranch_vccnz .Lkl_skip
; __device__ __forceinline__ void phase_mixer(const Params& p, LAS unsigned char* lds, int l, bool with_ctx, int G, int tid, int wave, int lane, int rep_attn, int rep_pool) {
;     ...
;             const int tok0 = b * SEQ + rs0 * 64;
;             const bf16_t* ksrc = PB + (size_t)(tok0 + (tid >> 3)) * PBW + 1024 + h * 64 + (tid & 7) * 8;
;             u32x4 kreg[9], vreg[9];
; #pragma unroll
;             for (int ps = 0; ps < 9; ++ps) { const int idx = ps * 512 + tid, d = idx / 72, ch = idx - d * 72;
;                 kreg[ps] = *(const u32x4*)(ksrc + (size_t)(ps * 64) * PBW);
;                 vreg[ps] = *(const u32x4*)(VT + (size_t)(h * 64 + d) * VTP + tok0 + ch * 8); }
	v_sub_u32_e64 v248, s71, 4 clamp
	v_min_u32_e32 v248, 56, v248
	v_lshlrev_b32_e32 v248, 6, v248
	v_or_b32_e32 v248, s76, v248
	v_add_u32_e32 v248, v248, v109
	v_mov_b64_e32 v[250:251], s[0:1]
	v_mad_i64_i32 v[250:251], s[98:99], v248, s58, v[250:251]
	s_lshl_b32 s30, s70, 1
	v_lshl_add_u64 v[250:251], v[250:251], 0, s[30:31]
	v_lshl_add_u64 v[250:251], v[250:251], 0, v[156:157]
	s_mov_b32 s99, 0
	global_load_dwordx4 v[216:219], v[250:251], off offset:2048
	s_mov_b32 s98, 0x30000
	v_lshl_add_u64 v[224:225], v[250:251], 0, s[98:99]
	global_load_dwordx4 v[224:227], v[224:225], off offset:2048
	s_mov_b32 s98, 0x60000
	v_lshl_add_u64 v[228:229], v[250:251], 0, s[98:99]
	global_load_dwordx4 v[228:231], v[228:229], off offset:2048
	s_mov_b32 s98, 0x90000
	v_lshl_add_u64 v[190:191], v[250:251], 0, s[98:99]
	global_load_dwordx4 v[190:193], v[190:191], off offset:2048
	s_mov_b32 s98, 0xc0000
	v_lshl_add_u64 v[194:195], v[250:251], 0, s[98:99]
	global_load_dwordx4 v[194:197], v[194:195], off offset:2048
	s_mov_b32 s98, 0xf0000
	v_lshl_add_u64 v[198:199], v[250:251], 0, s[98:99]
	global_load_dwordx4 v[198:201], v[198:199], off offset:2048
	s_mov_b32 s98, 0x120000
	v_lshl_add_u64 v[202:203], v[250:251], 0, s[98:99]
	global_load_dwordx4 v[202:205], v[202:203], off offset:2048
	s_mov_b32 s98, 0x150000
	v_lshl_add_u64 v[182:183], v[250:251], 0, s[98:99]
	global_load_dwordx4 v[182:185], v[182:183], off offset:2048
	s_mov_b32 s98, 0x180000
	v_lshl_add_u64 v[186:187], v[250:251], 0, s[98:99]
	global_load_dwordx4 v[186:189], v[186:187], off offset:2048
